# v11: v10 + diff-attention next-tile K/V addresses: per-copy constant folded into the scalar tile offset (SALU) instead of 64-bit VALU adds
# speedup vs baseline: 1.0252x; 1.0039x over previous
; template <int DQK, int DV, bool BIAS> ...
;     ...
;     u32x4 pw[4];
; #pragma unroll
;     for (int j = 0; j < TPB; ++j) { ATT_LOAD(j, j); ATT_STORE(j, j); }
; #pragma unroll
;     for (int j = 0; j < TPB; ++j) ATT_LOAD(TPB + j, j);
;     const float qp = (float)(qpos0 + r32);
; #pragma unroll 2
;     for (int g = 0; g < NG; ++g) {
;         const int pair = g & 1;
;         __syncthreads();
;         if (g + 1 < NG) {
; #pragma unroll
;             for (int j = 0; j < TPB; ++j) ATT_STORE((pair ^ 1) * TPB + j, j);
;             if (g + 2 < NG) {
; #pragma unroll
;                 for (int j = 0; j < TPB; ++j) ATT_LOAD((g + 2) * TPB + j, j);
;             }
;         }
.LBB0_576:
	s_cmp_lt_u32 s51, 62
	s_cselect_b64 s[44:45], -1, 0
	s_cmp_gt_u32 s51, 61
	s_waitcnt lgkmcnt(0)
	s_barrier
	s_waitcnt vmcnt(0)
	ds_write_b128 v168, v[138:141] offset:9216
	ds_write_b128 v171, v[130:133] offset:34816
	ds_write_b128 v171, v[134:137] offset:43008
	s_cbranch_scc1 .LBB0_578
	s_add_u32 s100, s6, 0xca000
	s_addc_u32 s101, s7, 0
	v_lshl_add_u64 v[82:83], v[148:149], 0, s[100:101]
	v_lshl_add_u64 v[84:85], v[146:147], 0, s[100:101]
	global_load_dwordx4 v[130:133], v[82:83], off offset:2048
	global_load_dwordx4 v[134:137], v[84:85], off offset:2048
	v_lshl_add_u64 v[82:83], v[144:145], 0, s[100:101]
	global_load_dwordx4 v[138:141], v[82:83], off offset:1024

; template <int DQK, int DV, bool BIAS> ...
;     ...
;     u32x4 pw[4];
; #pragma unroll
;     for (int j = 0; j < TPB; ++j) { ATT_LOAD(j, j); ATT_STORE(j, j); }
; #pragma unroll
;     for (int j = 0; j < TPB; ++j) ATT_LOAD(TPB + j, j);
;     const float qp = (float)(qpos0 + r32);
; #pragma unroll 2
;     for (int g = 0; g < NG; ++g) {
;         const int pair = g & 1;
;         __syncthreads();
;         if (g + 1 < NG) {
; #pragma unroll
;             for (int j = 0; j < TPB; ++j) ATT_STORE((pair ^ 1) * TPB + j, j);
;             if (g + 2 < NG) {
; #pragma unroll
;                 for (int j = 0; j < TPB; ++j) ATT_LOAD((g + 2) * TPB + j, j);
;             }
;         }
.Lend1_p4a1:
	s_cmp_eq_u32 s6, 0x1876000
	s_barrier
	s_cbranch_scc1 .LBB0_584
	s_andn2_b64 vcc, exec, s[44:45]
	s_waitcnt vmcnt(0)
	ds_write_b128 v168, v[138:141]
	ds_write_b128 v171, v[130:133] offset:18432
	ds_write_b128 v171, v[134:137] offset:26624
	s_cbranch_vccnz .LBB0_584
	s_add_u32 s100, s6, 0x12f000
	s_addc_u32 s101, s7, 0
	v_lshl_add_u64 v[98:99], v[148:149], 0, s[100:101]
	v_lshl_add_u64 v[100:101], v[146:147], 0, s[100:101]
	global_load_dwordx4 v[130:133], v[98:99], off offset:2048
	global_load_dwordx4 v[134:137], v[100:101], off offset:2048
	v_lshl_add_u64 v[98:99], v[144:145], 0, s[100:101]
	global_load_dwordx4 v[138:141], v[98:99], off offset:1024

; template <int DQK, int DV, bool BIAS> ...
;     ...
;     u32x4 pw[4];
; #pragma unroll
;     for (int j = 0; j < TPB; ++j) { ATT_LOAD(j, j); ATT_STORE(j, j); }
; #pragma unroll
;     for (int j = 0; j < TPB; ++j) ATT_LOAD(TPB + j, j);
;     const float qp = (float)(qpos0 + r32);
; #pragma unroll 2
;     for (int g = 0; g < NG; ++g) {
;         const int pair = g & 1;
;         __syncthreads();
;         if (g + 1 < NG) {
; #pragma unroll
;             for (int j = 0; j < TPB; ++j) ATT_STORE((pair ^ 1) * TPB + j, j);
;             if (g + 2 < NG) {
; #pragma unroll
;                 for (int j = 0; j < TPB; ++j) ATT_LOAD((g + 2) * TPB + j, j);
;             }
;         }
.LBB0_588:
	s_cmp_lt_u32 s7, 62
	s_cselect_b64 s[42:43], -1, 0
	s_cmp_gt_u32 s7, 61
	s_waitcnt lgkmcnt(0)
	s_barrier
	s_waitcnt vmcnt(0)
	ds_write_b128 v174, v[138:141] offset:9216
	ds_write_b128 v175, v[130:133] offset:34816
	ds_write_b128 v175, v[134:137] offset:43008
	s_cbranch_scc1 .LBB0_590
	s_add_u32 s100, s4, 0xca000
	s_addc_u32 s101, s5, 0
	v_lshl_add_u64 v[82:83], v[148:149], 0, s[100:101]
	v_lshl_add_u64 v[84:85], v[146:147], 0, s[100:101]
	global_load_dwordx4 v[130:133], v[82:83], off offset:2048
	global_load_dwordx4 v[134:137], v[84:85], off offset:2048
	v_lshl_add_u64 v[82:83], v[144:145], 0, s[100:101]
	global_load_dwordx4 v[138:141], v[82:83], off offset:1152

; template <int DQK, int DV, bool BIAS> ...
;     ...
;     u32x4 pw[4];
; #pragma unroll
;     for (int j = 0; j < TPB; ++j) { ATT_LOAD(j, j); ATT_STORE(j, j); }
; #pragma unroll
;     for (int j = 0; j < TPB; ++j) ATT_LOAD(TPB + j, j);
;     const float qp = (float)(qpos0 + r32);
; #pragma unroll 2
;     for (int g = 0; g < NG; ++g) {
;         const int pair = g & 1;
;         __syncthreads();
;         if (g + 1 < NG) {
; #pragma unroll
;             for (int j = 0; j < TPB; ++j) ATT_STORE((pair ^ 1) * TPB + j, j);
;             if (g + 2 < NG) {
; #pragma unroll
;                 for (int j = 0; j < TPB; ++j) ATT_LOAD((g + 2) * TPB + j, j);
;             }
;         }
.Lend1_p4a2:
	s_cmp_eq_u32 s4, 0x1876000
	s_barrier
	s_cbranch_scc1 .LBB0_596
	s_andn2_b64 vcc, exec, s[42:43]
	s_waitcnt vmcnt(0)
	ds_write_b128 v174, v[138:141]
	ds_write_b128 v175, v[130:133] offset:18432
	ds_write_b128 v175, v[134:137] offset:26624
	s_cbranch_vccnz .LBB0_596
	s_add_u32 s100, s4, 0x12f000
	s_addc_u32 s101, s5, 0
	v_lshl_add_u64 v[98:99], v[148:149], 0, s[100:101]
	v_lshl_add_u64 v[100:101], v[146:147], 0, s[100:101]
	global_load_dwordx4 v[130:133], v[98:99], off offset:2048
	global_load_dwordx4 v[134:137], v[100:101], off offset:2048
	v_lshl_add_u64 v[98:99], v[144:145], 0, s[100:101]
	global_load_dwordx4 v[138:141], v[98:99], off offset:1152

; #define LAS __attribute__((address_space(3)))
; __global__ void __launch_bounds__(512, 2) fwd_mega(Params Pv) {
;     extern __shared__ __attribute__((aligned(16))) unsigned char lds_raw[];
;     LAS unsigned char* lds = (LAS unsigned char*)lds_raw;
	.amdhsa_kernel _Z8fwd_mega6Params
		.amdhsa_group_segment_fixed_size 0
		.amdhsa_private_segment_fixed_size 0
		.amdhsa_kernarg_size 552
		.amdhsa_user_sgpr_count 2
		.amdhsa_user_sgpr_dispatch_ptr 0
		.amdhsa_user_sgpr_queue_ptr 0
		.amdhsa_user_sgpr_kernarg_segment_ptr 1
		.amdhsa_user_sgpr_dispatch_id 0
		.amdhsa_user_sgpr_kernarg_preload_length 0
		.amdhsa_user_sgpr_kernarg_preload_offset 0
		.amdhsa_user_sgpr_private_segment_size 0
		.amdhsa_uses_dynamic_stack 0
		.amdhsa_enable_private_segment 0
		.amdhsa_system_sgpr_workgroup_id_x 1
		.amdhsa_system_sgpr_workgroup_id_y 0
		.amdhsa_system_sgpr_workgroup_id_z 0
		.amdhsa_system_sgpr_workgroup_info 0
		.amdhsa_system_vgpr_workitem_id 2
		.amdhsa_next_free_vgpr 230
		.amdhsa_next_free_sgpr 102
		.amdhsa_accum_offset 232
		.amdhsa_reserve_vcc 1
		.amdhsa_float_round_mode_32 0
		.amdhsa_float_round_mode_16_64 0
		.amdhsa_float_denorm_mode_32 3
		.amdhsa_float_denorm_mode_16_64 3
		.amdhsa_dx10_clamp 1
		.amdhsa_ieee_mode 1
		.amdhsa_fp16_overflow 0
		.amdhsa_tg_split 0
		.amdhsa_exception_fp_ieee_invalid_op 0
		.amdhsa_exception_fp_denorm_src 0
		.amdhsa_exception_fp_ieee_div_zero 0
		.amdhsa_exception_fp_ieee_overflow 0
		.amdhsa_exception_fp_ieee_underflow 0
		.amdhsa_exception_fp_ieee_inexact 0
		.amdhsa_exception_int_div_zero 0
	.end_amdhsa_kernel

; #define LAS __attribute__((address_space(3)))
; __global__ void __launch_bounds__(512, 2) fwd_mega(Params Pv) {
;     extern __shared__ __attribute__((aligned(16))) unsigned char lds_raw[];
;     LAS unsigned char* lds = (LAS unsigned char*)lds_raw;
amdhsa.kernels:
  - .agpr_count:     0
    .args:
      - .offset:         0
        .size:           296
        .value_kind:     by_value
      - .offset:         296
        .size:           4
        .value_kind:     hidden_block_count_x
      - .offset:         300
        .size:           4
        .value_kind:     hidden_block_count_y
      - .offset:         304
        .size:           4
        .value_kind:     hidden_block_count_z
      - .offset:         308
        .size:           2
        .value_kind:     hidden_group_size_x
      - .offset:         310
        .size:           2
        .value_kind:     hidden_group_size_y
      - .offset:         312
        .size:           2
        .value_kind:     hidden_group_size_z
      - .offset:         314
        .size:           2
        .value_kind:     hidden_remainder_x
      - .offset:         316
        .size:           2
        .value_kind:     hidden_remainder_y
      - .offset:         318
        .size:           2
        .value_kind:     hidden_remainder_z
      - .offset:         336
        .size:           8
        .value_kind:     hidden_global_offset_x
      - .offset:         344
        .size:           8
        .value_kind:     hidden_global_offset_y
      - .offset:         352
        .size:           8
        .value_kind:     hidden_global_offset_z
      - .offset:         360
        .size:           2
        .value_kind:     hidden_grid_dims
      - .offset:         384
        .size:           8
        .value_kind:     hidden_multigrid_sync_arg
      - .offset:         416
        .size:           4
        .value_kind:     hidden_dynamic_lds_size
    .group_segment_fixed_size: 0
    .kernarg_segment_align: 8
    .kernarg_segment_size: 552
    .language:       OpenCL C
    .language_version:
      - 2
      - 0
    .max_flat_workgroup_size: 512
    .name:           _Z8fwd_mega6Params
    .private_segment_fixed_size: 0
    .sgpr_count:     108
    .sgpr_spill_count: 0
    .symbol:         _Z8fwd_mega6Params.kd
    .uniform_work_group_size: 1
    .uses_dynamic_stack: false
    .vgpr_count:     230
    .vgpr_spill_count: 0
    .wavefront_size: 64
